# convert_ffn moved before the barrier that follows the projection phase and its items handed out dynamically: wave 0 of a workgroup claims blocks of 8 items from one global counter (LDS broadcast), so
# speedup vs baseline: 1.0091x; 1.0073x over previous
.LBB0_854:
	v_mov_b32_e32 v35, v237
	s_mul_i32 s7, s56, 0x1600000
	v_readfirstlane_b32 s4, v35
	s_ashr_i32 s19, s4, 6
	v_readlane_b32 s4, v254, 0
	v_readfirstlane_b32 s100, v237
	s_cmp_gt_u32 s100, 63
	s_cbranch_scc1 .Lmy_cv2_w
	s_mov_b64 s[44:45], exec
	s_mov_b64 exec, 1
	s_lshl_b32 s100, s40, 8
	s_add_i32 s100, s100, 0x5000
	v_mov_b32_e32 v90, s100
	v_mov_b32_e32 v91, 1
	global_atomic_add v91, v90, v91, s[36:37] sc0
	v_mov_b32_e32 v90, 0x21008
	s_waitcnt vmcnt(0)
	ds_write_b32 v90, v91
	s_waitcnt lgkmcnt(0)
	s_mov_b64 exec, s[44:45]
.Lmy_cv2_w:
	s_barrier
	v_mov_b32_e32 v90, 0x21008
	ds_read_b32 v90, v90
	s_waitcnt lgkmcnt(0)
	s_barrier
	v_readfirstlane_b32 s18, v90
	v_readfirstlane_b32 s100, v237
	s_lshr_b32 s100, s100, 6
	s_lshl_b32 s18, s18, 3
	s_add_i32 s18, s18, s100
	s_load_dwordx2 s[4:5], s[0:1], 0x60
	s_load_dwordx2 s[10:11], s[0:1], 0x78
	s_load_dwordx2 s[8:9], s[0:1], 0x90
	s_mov_b32 s57, s43
	s_mul_hi_u32 s6, s56, 0x1600000
	v_and_b32_e32 v34, 63, v35
	s_waitcnt lgkmcnt(0)
	s_add_u32 s14, s4, s7
	s_addc_u32 s15, s5, s6
	s_lshl_b64 s[4:5], s[56:57], 12
	s_add_u32 s6, s8, s4
	s_addc_u32 s7, s9, s5
	s_mul_i32 s5, s56, 0xb00000
	s_mul_hi_u32 s4, s56, 0xb00000
	s_add_u32 s16, s10, s5
	s_addc_u32 s17, s11, s4
	s_cmpk_lt_i32 s18, 0x1080
	s_cselect_b64 s[10:11], -1, 0
	s_cmpk_gt_i32 s18, 0x107f
	v_lshrrev_b32_e32 v36, 5, v34
	s_cbranch_scc1 .LBB0_609
	s_cmpk_gt_i32 s18, 0xaff
	s_cselect_b64 s[4:5], -1, 0
	s_and_b64 s[12:13], s[4:5], exec
	s_cselect_b32 s20, 0x400, s3
	s_cselect_b32 s22, 0xfffff500, 0
	s_lshr_b32 s21, s20, 5
	s_abs_i32 s12, s21
	v_cvt_f32_u32_e32 v0, s12
	s_sub_i32 s24, 0, s12
	s_add_i32 s22, s22, s18
	s_abs_i32 s23, s22
	v_rcp_iflag_f32_e32 v0, v0
	s_xor_b32 s13, s22, s21
	s_ashr_i32 s13, s13, 31
	v_mov_b32_e32 v8, 1.0
	v_mul_f32_e32 v0, 0x4f7ffffe, v0
	v_cvt_u32_f32_e32 v0, v0
	s_nop 0
	v_readfirstlane_b32 s25, v0
	s_mul_i32 s24, s24, s25
	s_mul_hi_u32 s24, s25, s24
	s_add_i32 s25, s25, s24
	s_mul_hi_u32 s24, s23, s25
	s_mul_i32 s25, s24, s12
	s_sub_i32 s23, s23, s25
	s_add_i32 s26, s24, 1
	s_sub_i32 s25, s23, s12
	s_cmp_ge_u32 s23, s12
	s_cselect_b32 s24, s26, s24
	s_cselect_b32 s23, s25, s23
	s_add_i32 s25, s24, 1
	s_cmp_ge_u32 s23, s12
	s_cselect_b32 s12, s25, s24
	s_xor_b32 s12, s12, s13
	s_sub_i32 s23, s12, s13
	s_cmp_eq_u64 s[8:9], 0
	v_lshl_or_b32 v2, s23, 6, v36
	s_cselect_b64 s[12:13], -1, 0
	s_or_b64 s[12:13], s[4:5], s[12:13]
	v_ashrrev_i32_e32 v3, 31, v2
	s_and_b64 vcc, exec, s[12:13]
	v_lshl_add_u64 v[6:7], v[2:3], 2, s[6:7]
	v_mov_b32_e32 v3, 1.0
	s_cbranch_vccnz .LBB0_546
	global_load_dword v3, v[6:7], off

.LBB0_612:
	v_add_u32_e32 v35, 0x400, v42
	ds_write2_b32 v42, v2, v3 offset1:66
	ds_write2_b32 v42, v4, v5 offset0:132 offset1:198
	ds_write2_b32 v35, v6, v7 offset0:8 offset1:74
	ds_write2_b32 v35, v8, v9 offset0:140 offset1:206
	v_add_u32_e32 v35, 0x800, v42
	ds_write2_b32 v35, v10, v11 offset0:16 offset1:82
	ds_write2_b32 v35, v12, v13 offset0:148 offset1:214
	v_add_u32_e32 v35, 0xc00, v42
	v_readfirstlane_b32 s100, v237
	s_cmp_gt_u32 s100, 63
	s_cbranch_scc1 .Lmy_cv1_w
	s_mov_b64 s[44:45], exec
	s_mov_b64 exec, 1
	s_lshl_b32 s100, s40, 8
	s_add_i32 s100, s100, 0x5000
	v_mov_b32_e32 v90, s100
	v_mov_b32_e32 v91, 1
	global_atomic_add v91, v90, v91, s[36:37] sc0
	v_mov_b32_e32 v90, 0x21008
	s_waitcnt vmcnt(0)
	ds_write_b32 v90, v91
	s_waitcnt lgkmcnt(0)
	s_mov_b64 exec, s[44:45]
.Lmy_cv1_w:
	s_barrier
	v_mov_b32_e32 v90, 0x21008
	ds_read_b32 v90, v90
	s_waitcnt lgkmcnt(0)
	s_barrier
	v_readfirstlane_b32 s19, v90
	v_readfirstlane_b32 s100, v237
	s_lshr_b32 s100, s100, 6
	s_lshl_b32 s19, s19, 3
	s_add_i32 s19, s19, s100
	ds_write2_b32 v35, v14, v15 offset0:24 offset1:90
	ds_write2_b32 v35, v16, v17 offset0:156 offset1:222
	v_add_u32_e32 v35, 0x1000, v42
	ds_write2_b32 v35, v18, v19 offset0:32 offset1:98
	ds_write2_b32 v35, v20, v21 offset0:164 offset1:230
	v_add_u32_e32 v35, 0x1400, v42
	s_cmpk_gt_i32 s19, 0x107f
	ds_write2_b32 v35, v22, v23 offset0:40 offset1:106
	ds_write2_b32 v35, v24, v25 offset0:172 offset1:238
	v_add_u32_e32 v35, 0x1800, v42
	s_cselect_b64 s[10:11], -1, 0
	ds_write2_b32 v35, v26, v27 offset0:48 offset1:114
	ds_write2_b32 v35, v28, v29 offset0:180 offset1:246
	v_add_u32_e32 v35, 0x1c00, v42
	s_and_b64 vcc, exec, s[10:11]
	ds_write2_b32 v35, v30, v31 offset0:56 offset1:122
	ds_write2_b32 v35, v32, v33 offset0:188 offset1:254
	s_cbranch_vccnz .LBB0_678
	s_cmpk_gt_i32 s19, 0xaff
	s_cselect_b64 s[4:5], -1, 0
	s_and_b64 s[12:13], s[4:5], exec
	s_cselect_b32 s20, 0x400, s3
	s_cselect_b32 s12, 0xfffff500, 0
	s_lshr_b32 s21, s20, 5
	s_abs_i32 s13, s21
	v_cvt_f32_u32_e32 v2, s13
	s_sub_i32 s24, 0, s13
	s_add_i32 s22, s19, s12
	v_rcp_iflag_f32_e32 v2, v2
	s_abs_i32 s23, s22
	s_xor_b32 s12, s22, s21
	s_ashr_i32 s12, s12, 31
	v_mul_f32_e32 v2, 0x4f7ffffe, v2
	v_cvt_u32_f32_e32 v2, v2
	v_mov_b32_e32 v8, 1.0
	v_readfirstlane_b32 s25, v2
	s_mul_i32 s24, s24, s25
	s_mul_hi_u32 s24, s25, s24
	s_add_i32 s25, s25, s24
	s_mul_hi_u32 s24, s23, s25
	s_mul_i32 s25, s24, s13
	s_sub_i32 s23, s23, s25
	s_add_i32 s26, s24, 1
	s_sub_i32 s25, s23, s13
	s_cmp_ge_u32 s23, s13
	s_cselect_b32 s24, s26, s24
	s_cselect_b32 s23, s25, s23
	s_add_i32 s25, s24, 1
	s_cmp_ge_u32 s23, s13
	s_cselect_b32 s13, s25, s24
	s_xor_b32 s13, s13, s12
	s_sub_i32 s23, s13, s12
	v_lshl_or_b32 v2, s23, 6, v36
	s_or_b64 s[12:13], s[4:5], s[8:9]
	v_ashrrev_i32_e32 v3, 31, v2
	s_and_b64 vcc, exec, s[12:13]
	v_lshl_add_u64 v[6:7], v[2:3], 2, s[6:7]
	v_mov_b32_e32 v3, 1.0
	s_cbranch_vccnz .LBB0_615
	global_load_dword v3, v[6:7], off
